# prompt SGU unit: spatial-weight fragments of all k-steps prefetched during the gate-row normalisation, epilogue u-row loads issued together
# speedup vs baseline: 1.0089x; 1.0034x over previous
; #define LAS __attribute__((address_space(3)))
; __device__ __forceinline__ unsigned pk2(float lo, float hi) { const f32x2_t v = {lo, hi}; const bf16x2_t b = __builtin_convertvector(v, bf16x2_t); return __builtin_bit_cast(unsigned, b); }
; __global__ void __launch_bounds__(NWAVES * 64, 2) mega(Args args) {
;     ...
;                 {
;                     const int rr = tid >> 2, cs = (tid & 3) * 16; const float mean = stl[2 * rr], rstd = stl[2 * rr + 1];
;                     const u32x4* gp = (const u32x4*)(Gb + (R0 + rr) * 256 + g * 64 + cs);
;                     const float* sgp = sg + g * 64 + cs; const float* sbp = sb_ + g * 64 + cs;
; #pragma unroll
;                     for (int q = 0; q < 2; ++q) {
;                         const u32x4 raw = gp[q];
;                         const f32x4 g0 = *(const f32x4*)(sgp + 8 * q), g1 = *(const f32x4*)(sgp + 8 * q + 4), b0 = *(const f32x4*)(sbp + 8 * q), b1 = *(const f32x4*)(sbp + 8 * q + 4);
;                         const f32x4 v0 = ((f32x4){bflo(raw.x), bfhi(raw.x), bflo(raw.y), bfhi(raw.y)} - mean) * rstd * g0 + b0;
;                         const f32x4 v1 = ((f32x4){bflo(raw.z), bfhi(raw.z), bflo(raw.w), bfhi(raw.w)} - mean) * rstd * g1 + b1;
;                         u32x4 o; o.x = pk2(v0.x, v0.y); o.y = pk2(v0.z, v0.w); o.z = pk2(v1.x, v1.y); o.w = pk2(v1.z, v1.w);
;                         *(LAS u32x4*)(lds + rr * 160 + cs * 2 + q * 16) = o;
;                     }
;                 }
;                 __syncthreads();
;                 const int fr = lane & 15, fq = lane >> 4, mt = wave;
;                 f32x4 acc[4];
; #pragma unroll
;                 for (int n = 0; n < 4; ++n) acc[n] = (f32x4){0.f, 0.f, 0.f, 0.f};
;                 const bf16_t* wrow = WSP + (((size_t)l * 4 + g) * 128 + 16 * mt + fr) * 128;
;                 const LAS unsigned char* trp = lds + (4 * fq + (fr >> 2)) * 160 + (lane & 3) * 8;
;                 for (int sk = 0; sk <= (mt >> 1); ++sk) {
;                     const u32x2 w0 = *(const u32x2*)(wrow + 32 * sk + 4 * fq), w1 = *(const u32x2*)(wrow + 32 * sk + 16 + 4 * fq);
.LBB0_1764:
	s_or_b64 exec, exec, s[0:1]
	v_lshl_add_u64 v[4:5], s[38:39], 0, v[0:1]
	v_readlane_b32 s10, v252, 17
	s_and_b32 s1, s4, 3
	v_lshlrev_b64 v[4:5], 9, v[4:5]
	v_readlane_b32 s11, v252, 18
	s_lshl_b32 s4, s1, 7
	v_mov_b32_e32 v33, v2
	v_lshl_add_u64 v[4:5], s[10:11], 0, v[4:5]
	v_lshl_add_u64 v[4:5], v[4:5], 0, s[4:5]
	s_lshl_b32 s10, s1, 8
	s_mov_b32 s11, s5
	v_lshl_add_u64 v[8:9], v[4:5], 0, v[32:33]
	v_lshl_add_u64 v[44:45], v[22:23], 0, s[10:11]
	v_lshl_add_u64 v[60:61], v[24:25], 0, s[10:11]
	s_waitcnt lgkmcnt(0)
	s_barrier
	ds_read_b64 v[36:37], v20 offset:24576
	global_load_dwordx4 v[4:7], v[8:9], off offset:16
	s_nop 0
	global_load_dwordx4 v[8:11], v[8:9], off
	s_nop 0
	global_load_dwordx4 v[12:15], v[44:45], off offset:48
	global_load_dwordx4 v[16:19], v[44:45], off offset:32
	global_load_dwordx4 v[40:43], v[44:45], off offset:16
	s_nop 0
	global_load_dwordx4 v[44:47], v[44:45], off
	s_nop 0
	global_load_dwordx4 v[48:51], v[60:61], off offset:48
	global_load_dwordx4 v[52:55], v[60:61], off offset:32
	global_load_dwordx4 v[56:59], v[60:61], off offset:16
	s_nop 0
	global_load_dwordx4 v[60:63], v[60:61], off
	s_or_b32 s40, s6, s4
	v_add_u32_e32 v180, s40, v26
	v_mov_b32_e32 v181, v2
	v_lshlrev_b64 v[180:181], 8, v[180:181]
	v_lshl_add_u64 v[180:181], v[30:31], 0, v[180:181]
	global_load_dwordx2 v[146:147], v[180:181], off
	global_load_dwordx2 v[148:149], v[180:181], off offset:32
	global_load_dwordx2 v[150:151], v[180:181], off offset:64
	global_load_dwordx2 v[152:153], v[180:181], off offset:96
	global_load_dwordx2 v[198:199], v[180:181], off offset:128
	global_load_dwordx2 v[200:201], v[180:181], off offset:160
	global_load_dwordx2 v[202:203], v[180:181], off offset:192
	global_load_dwordx2 v[204:205], v[180:181], off offset:224
	s_lshl_b32 s0, s1, 6
	s_mov_b32 s41, s7
	v_readlane_b32 s1, v254, 63
	s_waitcnt vmcnt(16)
	v_lshlrev_b32_e32 v33, 16, v8
	v_and_b32_e32 v39, 0xffff0000, v8
	v_lshlrev_b32_e32 v8, 16, v9
	v_and_b32_e32 v9, 0xffff0000, v9
	s_waitcnt lgkmcnt(0)
	v_sub_f32_e32 v9, v9, v36
	v_sub_f32_e32 v8, v8, v36
	v_sub_f32_e32 v65, v39, v36
	v_sub_f32_e32 v64, v33, v36
	v_pk_mul_f32 v[64:65], v[36:37], v[64:65] op_sel:[1,0]
	v_pk_mul_f32 v[8:9], v[36:37], v[8:9] op_sel:[1,0]
	v_lshlrev_b32_e32 v33, 16, v10
	v_and_b32_e32 v39, 0xffff0000, v10
	v_lshlrev_b32_e32 v10, 16, v11
	v_and_b32_e32 v11, 0xffff0000, v11
	s_waitcnt vmcnt(8)
	v_pk_fma_f32 v[46:47], v[46:47], v[8:9], v[62:63]
	v_pk_fma_f32 v[8:9], v[44:45], v[64:65], v[60:61]
	v_sub_f32_e32 v11, v11, v36
	v_sub_f32_e32 v10, v10, v36
	v_sub_f32_e32 v45, v39, v36
	v_sub_f32_e32 v44, v33, v36
	v_pk_mul_f32 v[44:45], v[36:37], v[44:45] op_sel:[1,0]
	v_pk_mul_f32 v[10:11], v[36:37], v[10:11] op_sel:[1,0]
	v_cvt_pk_bf16_f32 v8, v8, v9
	v_pk_fma_f32 v[42:43], v[42:43], v[10:11], v[58:59]
	v_pk_fma_f32 v[10:11], v[40:41], v[44:45], v[56:57]
	v_cvt_pk_bf16_f32 v9, v46, v47
	v_cvt_pk_bf16_f32 v10, v10, v11
	v_cvt_pk_bf16_f32 v11, v42, v43
	ds_write_b128 v38, v[8:11]
	v_lshlrev_b32_e32 v8, 16, v4
	v_and_b32_e32 v9, 0xffff0000, v4
	v_lshlrev_b32_e32 v4, 16, v5
	v_and_b32_e32 v5, 0xffff0000, v5
	v_sub_f32_e32 v5, v5, v36
	v_sub_f32_e32 v4, v4, v36
	v_sub_f32_e32 v9, v9, v36
	v_sub_f32_e32 v8, v8, v36
	v_pk_mul_f32 v[8:9], v[36:37], v[8:9] op_sel:[1,0]
	v_pk_mul_f32 v[4:5], v[36:37], v[4:5] op_sel:[1,0]
	v_mov_b32_e32 v33, v3
	v_pk_fma_f32 v[10:11], v[18:19], v[4:5], v[54:55]
	v_pk_fma_f32 v[4:5], v[16:17], v[8:9], v[52:53]
	v_lshlrev_b32_e32 v8, 16, v6
	v_and_b32_e32 v9, 0xffff0000, v6
	v_lshlrev_b32_e32 v6, 16, v7
	v_and_b32_e32 v7, 0xffff0000, v7
	v_sub_f32_e32 v7, v7, v36
	v_sub_f32_e32 v6, v6, v36
	v_sub_f32_e32 v9, v9, v36
	v_sub_f32_e32 v8, v8, v36
	v_pk_mul_f32 v[8:9], v[36:37], v[8:9] op_sel:[1,0]
	v_pk_mul_f32 v[6:7], v[36:37], v[6:7] op_sel:[1,0]
	v_cvt_pk_bf16_f32 v4, v4, v5
	v_pk_fma_f32 v[14:15], v[14:15], v[6:7], v[50:51]
	v_pk_fma_f32 v[6:7], v[12:13], v[8:9], v[48:49]
	v_cvt_pk_bf16_f32 v5, v10, v11
	v_cvt_pk_bf16_f32 v6, v6, v7
	v_cvt_pk_bf16_f32 v7, v14, v15
	ds_write_b128 v38, v[4:7] offset:16
	v_add_u32_e32 v4, s40, v26
	v_mov_b32_e32 v5, v2
	v_lshlrev_b64 v[4:5], 8, v[4:5]
	v_lshl_add_u64 v[36:37], v[30:31], 0, v[4:5]
	v_mov_b32_e32 v4, 0
	v_mov_b32_e32 v5, v4
	v_mov_b32_e32 v6, v4
	v_mov_b32_e32 v7, v4
	v_mov_b32_e32 v8, v4
	v_mov_b32_e32 v9, v4
	v_mov_b32_e32 v10, v4
	v_mov_b32_e32 v11, v4
	v_mov_b32_e32 v12, v4
	v_mov_b32_e32 v13, v4
	v_mov_b32_e32 v14, v4
	v_mov_b32_e32 v15, v4
	v_mov_b32_e32 v16, v4
	v_mov_b32_e32 v17, v4
	v_mov_b32_e32 v18, v4
	v_mov_b32_e32 v19, v4
	s_waitcnt lgkmcnt(0)
	s_barrier
; __device__ __forceinline__ u32x2 pk4(f32x4 v) { u32x2 r; r.x = pk2(v.x, v.y); r.y = pk2(v.z, v.w); return r; }
; __global__ void __launch_bounds__(NWAVES * 64, 2) mega(Args args) {
;     ...
;                 for (int sk = 0; sk <= (mt >> 1); ++sk) {
;                     const u32x2 w0 = *(const u32x2*)(wrow + 32 * sk + 4 * fq), w1 = *(const u32x2*)(wrow + 32 * sk + 16 + 4 * fq);
;                     u32x4 wv; wv.x = w0.x; wv.y = w0.y; wv.z = w1.x; wv.w = w1.y;
;                     const bf16x8 wb = __builtin_bit_cast(bf16x8, wv);
; #pragma unroll
;                     for (int n = 0; n < 4; ++n) {
;                         const s16x4 lo = vtr(trp + sk * 32 * 160 + n * 32), hi = vtr(trp + sk * 32 * 160 + 16 * 160 + n * 32);
;                         bf16x8 va; va[0] = lo[0]; va[1] = lo[1]; va[2] = lo[2]; va[3] = lo[3]; va[4] = hi[0]; va[5] = hi[1]; va[6] = hi[2]; va[7] = hi[3];
;                         acc[n] = __builtin_amdgcn_mfma_f32_16x16x32_bf16(va, wb, acc[n], 0, 0, 0);
;                     }
;                 }
;                 const int t = 16 * mt + fr; const float bs = args.in[11][((size_t)l * 4 + g) * 128 + t];
; #pragma unroll
;                 for (int n = 0; n < 4; ++n) {
;                     const u32x2 ur = *(const u32x2*)(Ub + (R0 + t) * 256 + g * 64 + 16 * n + 4 * fq);
;                     const f32x4 u = (f32x4){bflo(ur.x), bfhi(ur.x), bflo(ur.y), bfhi(ur.y)};
;                     *(u32x2*)(CAT + (R0 + t) * DM + ATT + g * 64 + 16 * n + 4 * fq) = pk4(u * (acc[n] + bs));
;                 }
.LBB0_1765:
	v_add_u32_e32 v39, 0xfffff5a0, v33
	v_add_u32_e32 v46, 0xffffffa0, v33
	ds_read_b64_tr_b16 v[44:45], v39
	ds_read_b64_tr_b16 v[46:47], v46
	v_add_u32_e32 v39, 0xfffff5c0, v33
	s_add_i32 s1, s1, -1
	s_cmp_eq_u32 s1, 0
	s_waitcnt vmcnt(6) lgkmcnt(0)
	v_mfma_f32_16x16x32_bf16 v[16:19], v[44:47], v[146:149], v[16:19]
	ds_read_b64_tr_b16 v[44:45], v39
	v_subrev_u32_e32 v39, 64, v33
	ds_read_b64_tr_b16 v[46:47], v39
	v_add_u32_e32 v39, 0xfffff5e0, v33
	s_waitcnt lgkmcnt(0)
	v_mfma_f32_16x16x32_bf16 v[12:15], v[44:47], v[146:149], v[12:15]
	ds_read_b64_tr_b16 v[44:45], v39
	v_subrev_u32_e32 v39, 32, v33
	ds_read_b64_tr_b16 v[46:47], v39
	v_add_u32_e32 v39, 0xfffff600, v33
	s_waitcnt lgkmcnt(0)
	v_mfma_f32_16x16x32_bf16 v[8:11], v[44:47], v[146:149], v[8:11]
	ds_read_b64_tr_b16 v[44:45], v39
	ds_read_b64_tr_b16 v[46:47], v33
	v_add_u32_e32 v33, 0x1400, v33
	s_waitcnt lgkmcnt(0)
	v_mfma_f32_16x16x32_bf16 v[4:7], v[44:47], v[146:149], v[4:7]
	s_cbranch_scc1 .Lmy_sgu_done
	v_add_u32_e32 v39, 0xfffff5a0, v33
	v_add_u32_e32 v46, 0xffffffa0, v33
	ds_read_b64_tr_b16 v[44:45], v39
	ds_read_b64_tr_b16 v[46:47], v46
	v_add_u32_e32 v39, 0xfffff5c0, v33
	s_add_i32 s1, s1, -1
	s_cmp_eq_u32 s1, 0
	s_waitcnt vmcnt(4) lgkmcnt(0)
	v_mfma_f32_16x16x32_bf16 v[16:19], v[44:47], v[150:153], v[16:19]
	ds_read_b64_tr_b16 v[44:45], v39
	v_subrev_u32_e32 v39, 64, v33
	ds_read_b64_tr_b16 v[46:47], v39
	v_add_u32_e32 v39, 0xfffff5e0, v33
	s_waitcnt lgkmcnt(0)
	v_mfma_f32_16x16x32_bf16 v[12:15], v[44:47], v[150:153], v[12:15]
	ds_read_b64_tr_b16 v[44:45], v39
	v_subrev_u32_e32 v39, 32, v33
	ds_read_b64_tr_b16 v[46:47], v39
	v_add_u32_e32 v39, 0xfffff600, v33
	s_waitcnt lgkmcnt(0)
	v_mfma_f32_16x16x32_bf16 v[8:11], v[44:47], v[150:153], v[8:11]
	ds_read_b64_tr_b16 v[44:45], v39
	ds_read_b64_tr_b16 v[46:47], v33
	v_add_u32_e32 v33, 0x1400, v33
	s_waitcnt lgkmcnt(0)
	v_mfma_f32_16x16x32_bf16 v[4:7], v[44:47], v[150:153], v[4:7]
	s_cbranch_scc1 .Lmy_sgu_done
	v_add_u32_e32 v39, 0xfffff5a0, v33
	v_add_u32_e32 v46, 0xffffffa0, v33
	ds_read_b64_tr_b16 v[44:45], v39
	ds_read_b64_tr_b16 v[46:47], v46
	v_add_u32_e32 v39, 0xfffff5c0, v33
	s_add_i32 s1, s1, -1
	s_cmp_eq_u32 s1, 0
	s_waitcnt vmcnt(2) lgkmcnt(0)
	v_mfma_f32_16x16x32_bf16 v[16:19], v[44:47], v[198:201], v[16:19]
	ds_read_b64_tr_b16 v[44:45], v39
	v_subrev_u32_e32 v39, 64, v33
	ds_read_b64_tr_b16 v[46:47], v39
	v_add_u32_e32 v39, 0xfffff5e0, v33
	s_waitcnt lgkmcnt(0)
	v_mfma_f32_16x16x32_bf16 v[12:15], v[44:47], v[198:201], v[12:15]
	ds_read_b64_tr_b16 v[44:45], v39
	v_subrev_u32_e32 v39, 32, v33
	ds_read_b64_tr_b16 v[46:47], v39
	v_add_u32_e32 v39, 0xfffff600, v33
	s_waitcnt lgkmcnt(0)
	v_mfma_f32_16x16x32_bf16 v[8:11], v[44:47], v[198:201], v[8:11]
	ds_read_b64_tr_b16 v[44:45], v39
	ds_read_b64_tr_b16 v[46:47], v33
	v_add_u32_e32 v33, 0x1400, v33
	s_waitcnt lgkmcnt(0)
	v_mfma_f32_16x16x32_bf16 v[4:7], v[44:47], v[198:201], v[4:7]
	s_cbranch_scc1 .Lmy_sgu_done
	v_add_u32_e32 v39, 0xfffff5a0, v33
	v_add_u32_e32 v46, 0xffffffa0, v33
	ds_read_b64_tr_b16 v[44:45], v39
	ds_read_b64_tr_b16 v[46:47], v46
	v_add_u32_e32 v39, 0xfffff5c0, v33
	s_add_i32 s1, s1, -1
	s_cmp_eq_u32 s1, 0
	s_waitcnt vmcnt(0) lgkmcnt(0)
	v_mfma_f32_16x16x32_bf16 v[16:19], v[44:47], v[202:205], v[16:19]
	ds_read_b64_tr_b16 v[44:45], v39
	v_subrev_u32_e32 v39, 64, v33
	ds_read_b64_tr_b16 v[46:47], v39
	v_add_u32_e32 v39, 0xfffff5e0, v33
	s_waitcnt lgkmcnt(0)
	v_mfma_f32_16x16x32_bf16 v[12:15], v[44:47], v[202:205], v[12:15]
	ds_read_b64_tr_b16 v[44:45], v39
	v_subrev_u32_e32 v39, 32, v33
	ds_read_b64_tr_b16 v[46:47], v39
	v_add_u32_e32 v39, 0xfffff600, v33
	s_waitcnt lgkmcnt(0)
	v_mfma_f32_16x16x32_bf16 v[8:11], v[44:47], v[202:205], v[8:11]
	ds_read_b64_tr_b16 v[44:45], v39
	ds_read_b64_tr_b16 v[46:47], v33
	v_add_u32_e32 v33, 0x1400, v33
	s_waitcnt lgkmcnt(0)
	v_mfma_f32_16x16x32_bf16 v[4:7], v[44:47], v[202:205], v[4:7]
.Lmy_sgu_done:
	v_lshl_add_u64 v[40:41], s[38:39], 0, v[26:27]
	v_readlane_b32 s10, v252, 15
	v_lshlrev_b64 v[42:43], 9, v[40:41]
	v_readlane_b32 s11, v252, 16
	s_lshl_b32 s4, s0, 1
	v_lshl_add_u64 v[36:37], s[40:41], 2, v[28:29]
	v_lshl_add_u64 v[42:43], s[10:11], 0, v[42:43]
	v_lshl_add_u64 v[42:43], v[42:43], 0, s[4:5]
	v_lshl_add_u64 v[42:43], v[42:43], 0, v[34:35]
	global_load_dword v36, v[36:37], off
	v_lshlrev_b64 v[40:41], 11, v[40:41]
	global_load_dwordx2 v[44:45], v[42:43], off
	global_load_dwordx2 v[146:147], v[42:43], off offset:32
	global_load_dwordx2 v[148:149], v[42:43], off offset:64
	global_load_dwordx2 v[150:151], v[42:43], off offset:96
	v_lshl_add_u64 v[40:41], s[74:75], 0, v[40:41]
	v_lshl_add_u64 v[40:41], v[40:41], 0, s[4:5]
	v_lshl_add_u64 v[40:41], v[40:41], 0, v[34:35]
	s_add_i32 s8, s8, 1
	s_cmp_eq_u32 s8, s2
	s_waitcnt vmcnt(4)
	v_pk_add_f32 v[16:17], v[36:37], v[16:17] op_sel_hi:[0,1]
	v_pk_add_f32 v[18:19], v[36:37], v[18:19] op_sel_hi:[0,1]
	s_waitcnt vmcnt(3)
	v_lshlrev_b32_e32 v46, 16, v44
	v_and_b32_e32 v47, 0xffff0000, v44
	v_lshlrev_b32_e32 v44, 16, v45
	v_and_b32_e32 v45, 0xffff0000, v45
	v_pk_mul_f32 v[18:19], v[18:19], v[44:45]
	v_pk_mul_f32 v[16:17], v[16:17], v[46:47]
	v_pk_add_f32 v[12:13], v[36:37], v[12:13] op_sel_hi:[0,1]
	v_cvt_pk_bf16_f32 v16, v16, v17
	v_cvt_pk_bf16_f32 v17, v18, v19
	global_store_dwordx2 v[40:41], v[16:17], off offset:1536
	s_waitcnt vmcnt(2)
	v_mov_b64_e32 v[16:17], v[146:147]
	v_pk_add_f32 v[14:15], v[36:37], v[14:15] op_sel_hi:[0,1]
	v_pk_add_f32 v[8:9], v[36:37], v[8:9] op_sel_hi:[0,1]
	v_pk_add_f32 v[10:11], v[36:37], v[10:11] op_sel_hi:[0,1]
	v_pk_add_f32 v[4:5], v[36:37], v[4:5] op_sel_hi:[0,1]
	v_pk_add_f32 v[6:7], v[36:37], v[6:7] op_sel_hi:[0,1]
	v_lshlrev_b32_e32 v18, 16, v16
	v_and_b32_e32 v19, 0xffff0000, v16
	v_lshlrev_b32_e32 v16, 16, v17
	v_and_b32_e32 v17, 0xffff0000, v17
	v_pk_mul_f32 v[14:15], v[14:15], v[16:17]
	v_pk_mul_f32 v[12:13], v[12:13], v[18:19]
	s_nop 0
	v_cvt_pk_bf16_f32 v12, v12, v13
	v_cvt_pk_bf16_f32 v13, v14, v15
	global_store_dwordx2 v[40:41], v[12:13], off offset:1568
	s_waitcnt vmcnt(1)
	v_mov_b64_e32 v[12:13], v[148:149]
	v_lshlrev_b32_e32 v14, 16, v12
	v_and_b32_e32 v15, 0xffff0000, v12
	v_lshlrev_b32_e32 v12, 16, v13
	v_and_b32_e32 v13, 0xffff0000, v13
	v_pk_mul_f32 v[10:11], v[10:11], v[12:13]
	v_pk_mul_f32 v[8:9], v[8:9], v[14:15]
	s_nop 0
	v_cvt_pk_bf16_f32 v8, v8, v9
	v_cvt_pk_bf16_f32 v9, v10, v11
	global_store_dwordx2 v[40:41], v[8:9], off offset:1600
	s_waitcnt vmcnt(0)
	v_mov_b64_e32 v[8:9], v[150:151]
	v_lshlrev_b32_e32 v10, 16, v8
	v_and_b32_e32 v11, 0xffff0000, v8
	v_lshlrev_b32_e32 v8, 16, v9
	v_and_b32_e32 v9, 0xffff0000, v9
	v_pk_mul_f32 v[6:7], v[6:7], v[8:9]
	v_pk_mul_f32 v[4:5], v[4:5], v[10:11]
	s_nop 0
	v_cvt_pk_bf16_f32 v4, v4, v5
	v_cvt_pk_bf16_f32 v5, v6, v7
	global_store_dwordx2 v[40:41], v[4:5], off offset:1632
	s_cbranch_scc0 .LBB0_1758
